# prep2: previous-row and xa loads also issued with the row loads at the loop top (no wait coupled to the SA/SB stores)
# speedup vs baseline: 1.0230x; 1.0028x over previous
; __device__ __forceinline__ float sigmoid_f(float x) { return __builtin_amdgcn_rcpf(1.0f + __expf(-x)); }
; __device__ __forceinline__ void prep2_phase(const Args& a, int e) {
;     ...
;         float lw[8], la[8], u[8], av[8], kk[8], km[8], ka[8];
;         unpack8(*(const v4u*)(Lw + (size_t)m * 512 + c8), lw); unpack8(*(const v4u*)(La + (size_t)m * 512 + c8), la);
;         float ss = 0.f;
; #pragma unroll
;         for (int i = 0; i < 8; ++i) {
;             u[i] = 1.0f - __expf(-0.6065306597126334f * sigmoid_f(w0[i] + lw[i]));
;             av[i] = sigmoid_f(a0[i] + la[i]);
;             kk[i] = k[i] * kkw[i]; ss += kk[i] * kk[i];
;             km[i] = k[i] * (1.0f + (av[i] - 1.0f) * kaw[i]);
;         }
.LBB0_265:
	s_or_b64 exec, exec, s[0:1]
	v_lshl_add_u64 v[130:131], s[22:23], 0, v[96:97]
	s_mov_b32 s0, 0xe780000
	v_add_co_u32_e32 v126, vcc, s0, v130
	s_mov_b32 s0, 0x12880000
	s_nop 0
	v_addc_co_u32_e32 v127, vcc, 0, v131, vcc
	s_waitcnt vmcnt(0)
	v_mov_b32_e32 v126, v64
	v_mov_b32_e32 v127, v65
	v_mov_b32_e32 v128, v66
	v_mov_b32_e32 v129, v67
	v_add_u32_e32 v62, s64, v62
	v_lshl_add_u64 v[96:97], v[96:97], 0, s[36:37]
	s_waitcnt vmcnt(0)
	v_lshlrev_b32_e32 v63, 16, v126
	v_and_b32_e32 v133, 0xffff0000, v126
	v_add_co_u32_e32 v126, vcc, s0, v130
	v_lshlrev_b32_e32 v141, 16, v127
	v_and_b32_e32 v143, 0xffff0000, v127
	v_addc_co_u32_e32 v127, vcc, 0, v131, vcc
	v_lshlrev_b32_e32 v149, 16, v128
	v_and_b32_e32 v145, 0xffff0000, v128
	v_lshlrev_b32_e32 v138, 16, v129
	v_and_b32_e32 v136, 0xffff0000, v129
	s_waitcnt vmcnt(0)
	v_mov_b32_e32 v126, v68
	v_mov_b32_e32 v127, v69
	v_mov_b32_e32 v128, v70
	v_mov_b32_e32 v129, v71
	v_add_f32_e32 v63, v26, v63
	v_mul_f32_e32 v63, 0xbfb8aa3b, v63
	v_exp_f32_e32 v63, v63
	v_add_f32_e32 v145, v31, v145
	v_mul_f32_e32 v145, 0xbfb8aa3b, v145
	v_exp_f32_e32 v145, v145
	v_add_f32_e32 v63, 1.0, v63
	v_rcp_f32_e32 v63, v63
	s_mov_b32 s0, 0x1aa80000
	v_add_f32_e32 v145, 1.0, v145
	v_rcp_f32_e32 v145, v145
	v_mul_f32_e32 v63, 0xbf1b4598, v63
	v_mul_f32_e32 v63, 0x3fb8aa3b, v63
	v_exp_f32_e32 v63, v63
	v_mul_f32_e32 v145, 0xbf1b4598, v145
	v_mul_f32_e32 v145, 0x3fb8aa3b, v145
	v_exp_f32_e32 v145, v145
	v_sub_f32_e32 v132, 1.0, v63
	v_sub_f32_e32 v145, 1.0, v145
	s_waitcnt vmcnt(0)
	v_lshlrev_b32_e32 v131, 16, v127
	v_and_b32_e32 v147, 0xffff0000, v127
	v_add_f32_e32 v127, v27, v133
	v_mul_f32_e32 v127, 0xbfb8aa3b, v127
	v_exp_f32_e32 v127, v127
	v_lshlrev_b32_e32 v130, 16, v126
	v_add_f32_e32 v63, v34, v130
	v_and_b32_e32 v126, 0xffff0000, v126
	v_mul_f32_e32 v63, 0xbfb8aa3b, v63
	v_exp_f32_e32 v63, v63
	v_add_f32_e32 v127, 1.0, v127
	v_add_f32_e32 v126, v35, v126
	v_rcp_f32_e32 v127, v127
	v_mul_f32_e32 v126, 0xbfb8aa3b, v126
	v_exp_f32_e32 v126, v126
	v_add_f32_e32 v63, 1.0, v63
	v_rcp_f32_e32 v134, v63
	v_mul_f32_e32 v127, 0xbf1b4598, v127
	v_mul_f32_e32 v127, 0x3fb8aa3b, v127
	v_add_f32_e32 v126, 1.0, v126
	v_exp_f32_e32 v127, v127
	v_rcp_f32_e32 v135, v126
	v_add_f32_e32 v63, -1.0, v134
	v_fma_f32 v63, v42, v63, 1.0
	v_mul_f32_e32 v63, v124, v63
	v_sub_f32_e32 v133, 1.0, v127
	v_pk_mul_f32 v[126:127], v[54:55], v[124:125]
	v_add_f32_e32 v124, -1.0, v135
	v_fma_f32 v124, v43, v124, 1.0
	v_mul_f32_e32 v140, v125, v124
	v_add_f32_e32 v124, v28, v141
	v_mul_f32_e32 v124, 0xbfb8aa3b, v124
	v_exp_f32_e32 v124, v124
	v_lshlrev_b32_e32 v148, 16, v128
	v_add_f32_e32 v148, v38, v148
	v_and_b32_e32 v146, 0xffff0000, v128
	v_add_f32_e32 v124, 1.0, v124
	v_rcp_f32_e32 v124, v124
	v_mul_f32_e32 v148, 0xbfb8aa3b, v148
	v_exp_f32_e32 v148, v148
	v_add_f32_e32 v146, v39, v146
	v_mul_f32_e32 v124, 0xbf1b4598, v124
	v_mul_f32_e32 v124, 0x3fb8aa3b, v124
	v_exp_f32_e32 v124, v124
	v_mul_f32_e32 v146, 0xbfb8aa3b, v146
	v_exp_f32_e32 v146, v146
	v_add_f32_e32 v148, 1.0, v148
	v_sub_f32_e32 v142, 1.0, v124
	v_add_f32_e32 v124, v36, v131
	v_mul_f32_e32 v124, 0xbfb8aa3b, v124
	v_exp_f32_e32 v124, v124
	v_rcp_f32_e32 v158, v148
	v_add_f32_e32 v146, 1.0, v146
	v_rcp_f32_e32 v146, v146
	v_add_f32_e32 v124, 1.0, v124
	v_rcp_f32_e32 v144, v124
	v_add_f32_e32 v148, -1.0, v158
	v_fma_f32 v148, v46, v148, 1.0
	v_mul_f32_e32 v160, v118, v148
	v_add_f32_e32 v124, -1.0, v144
	v_fma_f32 v124, v44, v124, 1.0
	v_mul_f32_e32 v141, v122, v124
	v_add_f32_e32 v124, v29, v143
	v_mul_f32_e32 v124, 0xbfb8aa3b, v124
	v_exp_f32_e32 v124, v124
	v_lshlrev_b32_e32 v139, 16, v129
	v_and_b32_e32 v137, 0xffff0000, v129
	v_pk_mul_f32 v[128:129], v[126:127], v[126:127]
	v_add_f32_e32 v124, 1.0, v124
	v_rcp_f32_e32 v124, v124
	s_nop 0
	v_mul_f32_e32 v124, 0xbf1b4598, v124
	v_mul_f32_e32 v124, 0x3fb8aa3b, v124
	v_exp_f32_e32 v124, v124
	s_nop 0
	v_sub_f32_e32 v143, 1.0, v124
	v_add_f32_e32 v124, v37, v147
	v_mul_f32_e32 v124, 0xbfb8aa3b, v124
	v_exp_f32_e32 v124, v124
	s_nop 0
	v_add_f32_e32 v124, 1.0, v124
	v_rcp_f32_e32 v147, v124
	v_pk_mul_f32 v[124:125], v[56:57], v[122:123]
	v_add_f32_e32 v122, -1.0, v147
	v_fma_f32 v122, v45, v122, 1.0
	v_mul_f32_e32 v122, v123, v122
	v_add_f32_e32 v123, v30, v149
	v_pk_mul_f32 v[148:149], v[58:59], v[118:119]
	v_add_f32_e32 v118, -1.0, v146
	v_fma_f32 v118, v47, v118, 1.0
	v_mul_f32_e32 v161, v119, v118
	v_add_f32_e32 v118, v32, v138
	v_mul_f32_e32 v118, 0xbfb8aa3b, v118
	v_exp_f32_e32 v118, v118
	v_pk_mul_f32 v[130:131], v[124:125], v[124:125]
	v_pk_mul_f32 v[156:157], v[148:149], v[148:149]
	v_mul_f32_e32 v123, 0xbfb8aa3b, v123
	v_add_f32_e32 v118, 1.0, v118
	v_rcp_f32_e32 v118, v118
	v_exp_f32_e32 v123, v123
	v_mul_f32_e32 v118, 0xbf1b4598, v118
	v_mul_f32_e32 v118, 0x3fb8aa3b, v118
	v_exp_f32_e32 v118, v118
	v_add_f32_e32 v123, 1.0, v123
	v_rcp_f32_e32 v123, v123
	v_sub_f32_e32 v138, 1.0, v118
	v_add_f32_e32 v118, v40, v139
	v_mul_f32_e32 v118, 0xbfb8aa3b, v118
	v_exp_f32_e32 v118, v118
	v_mul_f32_e32 v123, 0xbf1b4598, v123
	v_mul_f32_e32 v123, 0x3fb8aa3b, v123
	v_exp_f32_e32 v123, v123
	v_add_f32_e32 v118, 1.0, v118
	v_rcp_f32_e32 v139, v118
	v_sub_f32_e32 v123, 1.0, v123
	v_add_f32_e32 v118, -1.0, v139
	v_fma_f32 v118, v48, v118, 1.0
	v_mul_f32_e32 v162, v102, v118
	v_add_f32_e32 v118, v33, v136
	v_mul_f32_e32 v118, 0xbfb8aa3b, v118
	v_exp_f32_e32 v118, v118
	s_nop 0
	v_add_f32_e32 v118, 1.0, v118
	v_rcp_f32_e32 v118, v118
	s_nop 0
	v_mul_f32_e32 v118, 0xbf1b4598, v118
	v_mul_f32_e32 v118, 0x3fb8aa3b, v118
	v_exp_f32_e32 v118, v118
	s_nop 0
	v_sub_f32_e32 v163, 1.0, v118
	v_add_f32_e32 v118, v41, v137
; __device__ __forceinline__ float sum8_dpp(float x) { x += DPPX(x, 0xB1); x += DPPX(x, 0x4E); x += DPPX(x, 0x141); return x; }
; __device__ __forceinline__ void prep2_phase(const Args& a, int e) {
;     ...
;         ss = sum8_dpp(ss);
;         const float rn = rsqrtf(ss + 1e-12f);
; #pragma unroll
;         for (int i = 0; i < 8; ++i) { kk[i] *= rn; ka[i] = kk[i] * av[i]; }
;         bf16* sa = SA + ((size_t)m * 8 + h) * 256 + (lane & 7) * 8; bf16* sb = SB + ((size_t)m * 8 + h) * 128 + (lane & 7) * 8;
;         *(v4u*)(sa) = pack8(r); *(v4u*)(sa + 64) = pack8(u); *(v4u*)(sa + 128) = pack8(km); *(v4u*)(sa + 192) = pack8(v);
;         *(v4u*)(sb) = pack8(kk); *(v4u*)(sb + 64) = pack8(ka);
;         bf16* pb = PB + (size_t)m * APROJ + 1536;
;         float xa[16]; unpack8(*(const v4u*)(pb), xa); unpack8(*(const v4u*)(pb + 8), xa + 8);
;         f32x4 acc = ab;
; #pragma unroll
;         for (int i = 0; i < 16; ++i) { const f32x4 wv = *(const f32x4*)(aup + i * 256 + 4 * lane); acc += xa[i] * wv; }
	v_mul_f32_e32 v118, 0xbfb8aa3b, v118
	v_exp_f32_e32 v118, v118
	s_nop 0
	v_add_f32_e32 v118, 1.0, v118
	v_rcp_f32_e32 v164, v118
	v_pk_mul_f32 v[118:119], v[60:61], v[102:103]
	v_add_f32_e32 v102, v128, v129
	v_add_f32_e32 v102, v130, v102
	v_add_f32_e32 v102, v131, v102
	v_add_f32_e32 v102, v156, v102
	v_pk_mul_f32 v[136:137], v[118:119], v[118:119]
	v_add_f32_e32 v102, v157, v102
	v_add_f32_e32 v102, v136, v102
	v_add_f32_e32 v102, v137, v102
	v_add_f32_e32 v128, -1.0, v164
	v_fma_f32 v128, v49, v128, 1.0
	v_add_f32_dpp v102, v102, v102 quad_perm:[1,0,3,2] row_mask:0xf bank_mask:0xf bound_ctrl:1
	v_mul_f32_e32 v128, v103, v128
	s_nop 0
	v_add_f32_dpp v102, v102, v102 quad_perm:[2,3,0,1] row_mask:0xf bank_mask:0xf bound_ctrl:1
	s_nop 1
	v_add_f32_dpp v102, v102, v102 row_half_mirror row_mask:0xf bank_mask:0xf bound_ctrl:1
	v_add_f32_e32 v102, 0x2b8cbccc, v102
	v_cmp_gt_f32_e32 vcc, s50, v102
	v_mul_f32_e32 v103, 0x4b800000, v102
	s_nop 0
	v_cndmask_b32_e32 v102, v102, v103, vcc
	v_rsq_f32_e32 v102, v102
	s_nop 0
	v_mul_f32_e32 v103, 0x45800000, v102
	v_cndmask_b32_e32 v102, v102, v103, vcc
	v_mul_f32_e32 v126, v126, v102
	v_mul_f32_e32 v127, v127, v102
	v_mul_f32_e32 v124, v124, v102
	v_mul_f32_e32 v125, v125, v102
	v_mul_f32_e32 v137, v149, v102
	v_mul_f32_e32 v129, v134, v126
	v_mul_f32_e32 v130, v135, v127
	v_mul_f32_e32 v131, v144, v124
	v_mul_f32_e32 v134, v147, v125
	v_mul_f32_e32 v135, v148, v102
	v_mul_f32_e32 v144, v146, v137
	v_mul_f32_e32 v146, v118, v102
	v_mul_f32_e32 v147, v119, v102
	v_cvt_pk_bf16_f32 v102, v106, v107
	v_cvt_pk_bf16_f32 v103, v104, v105
	v_cvt_pk_bf16_f32 v104, v110, v111
	v_cvt_pk_bf16_f32 v105, v108, v109
	global_store_dwordx4 v[94:95], v[102:105], off
	v_lshl_add_u64 v[118:119], s[22:23], 0, v[90:91]
	v_add_co_u32_e32 v106, vcc, s0, v118
	v_cvt_pk_bf16_f32 v102, v132, v133
	v_cvt_pk_bf16_f32 v103, v142, v143
	v_cvt_pk_bf16_f32 v104, v123, v145
	v_cvt_pk_bf16_f32 v105, v138, v163
	global_store_dwordx4 v[94:95], v[102:105], off offset:128
	s_nop 0
	v_addc_co_u32_e32 v107, vcc, 0, v119, vcc
	v_cvt_pk_bf16_f32 v102, v63, v140
	v_cvt_pk_bf16_f32 v103, v141, v122
	v_cvt_pk_bf16_f32 v104, v160, v161
	v_cvt_pk_bf16_f32 v105, v162, v128
	global_store_dwordx4 v[94:95], v[102:105], off offset:256
	v_mul_f32_e32 v136, v158, v135
	v_mul_f32_e32 v139, v139, v146
	v_cvt_pk_bf16_f32 v102, v112, v113
	v_cvt_pk_bf16_f32 v103, v114, v115
	v_cvt_pk_bf16_f32 v104, v116, v117
	v_cvt_pk_bf16_f32 v105, v120, v121
	global_store_dwordx4 v[94:95], v[102:105], off offset:384
	v_mul_f32_e32 v148, v164, v147
	v_lshl_add_u64 v[90:91], v[90:91], 0, s[18:19]
	v_cvt_pk_bf16_f32 v102, v126, v127
	v_cvt_pk_bf16_f32 v103, v124, v125
	v_cvt_pk_bf16_f32 v104, v135, v137
	v_cvt_pk_bf16_f32 v105, v146, v147
	global_store_dwordx4 v[106:107], v[102:105], off
	v_lshl_add_u64 v[94:95], v[94:95], 0, s[28:29]
	s_nop 0
	v_cvt_pk_bf16_f32 v102, v129, v130
	v_cvt_pk_bf16_f32 v103, v131, v134
	v_cvt_pk_bf16_f32 v104, v136, v144
	v_cvt_pk_bf16_f32 v105, v139, v148
	global_store_dwordx4 v[106:107], v[102:105], off offset:128
	s_nop 1
	v_lshl_add_u64 v[102:103], s[22:23], 0, v[92:93]
	v_lshl_add_u64 v[106:107], v[102:103], 0, s[68:69]
	v_add_co_u32_e32 v102, vcc, s42, v102
	s_nop 1
	v_addc_co_u32_e32 v103, vcc, 0, v103, vcc
	v_mov_b32_e32 v102, v72
	v_mov_b32_e32 v103, v73
	v_mov_b32_e32 v104, v74
	v_mov_b32_e32 v105, v75
	s_nop 0
	v_mov_b32_e32 v106, v76
	v_mov_b32_e32 v107, v77
	v_mov_b32_e32 v108, v182
	v_mov_b32_e32 v109, v183
	v_lshlrev_b32_e32 v118, 16, v104
	v_and_b32_e32 v120, 0xffff0000, v104
	v_lshlrev_b32_e32 v122, 16, v105
	v_and_b32_e32 v124, 0xffff0000, v105
	v_lshlrev_b32_e32 v126, 16, v106
	v_and_b32_e32 v128, 0xffff0000, v106
	v_lshlrev_b32_e32 v130, 16, v107
	v_and_b32_e32 v132, 0xffff0000, v107
	s_nop 0
	v_lshlrev_b32_e32 v110, 16, v102
	v_and_b32_e32 v112, 0xffff0000, v102
	v_lshlrev_b32_e32 v114, 16, v103
	v_and_b32_e32 v116, 0xffff0000, v103
	v_lshlrev_b32_e32 v134, 16, v108
	v_and_b32_e32 v108, 0xffff0000, v108
	v_lshlrev_b32_e32 v136, 16, v109
	v_and_b32_e32 v102, 0xffff0000, v109
	v_pk_fma_f32 v[138:139], v[206:207], v[110:111], v[50:51] op_sel_hi:[1,0,1]
	v_pk_fma_f32 v[110:111], v[208:209], v[110:111], v[52:53] op_sel_hi:[1,0,1]
	s_nop 0
	v_pk_fma_f32 v[110:111], v[212:213], v[112:113], v[110:111] op_sel_hi:[1,0,1]
	v_pk_fma_f32 v[112:113], v[210:211], v[112:113], v[138:139] op_sel_hi:[1,0,1]
	s_nop 0
	v_pk_fma_f32 v[112:113], v[214:215], v[114:115], v[112:113] op_sel_hi:[1,0,1]
	v_pk_fma_f32 v[110:111], v[216:217], v[114:115], v[110:111] op_sel_hi:[1,0,1]
	s_nop 0
	v_pk_fma_f32 v[110:111], v[220:221], v[116:117], v[110:111] op_sel_hi:[1,0,1]
	v_pk_fma_f32 v[112:113], v[218:219], v[116:117], v[112:113] op_sel_hi:[1,0,1]
	s_nop 0
	v_pk_fma_f32 v[112:113], v[118:119], v[222:223], v[112:113] op_sel_hi:[0,1,1]
	v_pk_fma_f32 v[110:111], v[118:119], v[224:225], v[110:111] op_sel_hi:[0,1,1]
	s_nop 0
	v_pk_fma_f32 v[110:111], v[120:121], v[228:229], v[110:111] op_sel_hi:[0,1,1]
	v_pk_fma_f32 v[112:113], v[120:121], v[226:227], v[112:113] op_sel_hi:[0,1,1]
	s_nop 0
	v_pk_fma_f32 v[112:113], v[122:123], v[230:231], v[112:113] op_sel_hi:[0,1,1]
	v_pk_fma_f32 v[110:111], v[122:123], v[232:233], v[110:111] op_sel_hi:[0,1,1]
	s_nop 0
	v_pk_fma_f32 v[110:111], v[124:125], v[236:237], v[110:111] op_sel_hi:[0,1,1]
	v_pk_fma_f32 v[112:113], v[124:125], v[234:235], v[112:113] op_sel_hi:[0,1,1]
	s_nop 0
	v_pk_fma_f32 v[112:113], v[126:127], v[238:239], v[112:113] op_sel_hi:[0,1,1]
	v_pk_fma_f32 v[110:111], v[126:127], v[240:241], v[110:111] op_sel_hi:[0,1,1]
	s_nop 0
	v_pk_fma_f32 v[110:111], v[128:129], v[244:245], v[110:111] op_sel_hi:[0,1,1]
; __device__ __forceinline__ unsigned cvt_pk_bf16(float lo, float hi) { unsigned r; asm volatile("v_cvt_pk_bf16_f32 %0, %1, %2" : "=v"(r) : "v"(lo), "v"(hi)); return r; }
; __device__ __forceinline__ float softplus_f(float x) { return fmaxf(x, 0.f) + __logf(1.0f + __expf(-fabsf(x))); }
; __device__ __forceinline__ void prep2_phase(const Args& a, int e) {
;     ...
;         float ug[4];
; #pragma unroll
;         for (int i = 0; i < 4; ++i) ug[i] = 1.0f - __expf(-softplus_f(-acc[i]) * (1.0f / 16.0f));
;         v2u o; o.x = cvt_pk_bf16(ug[0], ug[1]); o.y = cvt_pk_bf16(ug[2], ug[3]);
;         *(v2u*)(pb + 4 * lane) = o;
	v_pk_fma_f32 v[112:113], v[128:129], v[242:243], v[112:113] op_sel_hi:[0,1,1]
	s_nop 0
	v_pk_fma_f32 v[112:113], v[130:131], v[246:247], v[112:113] op_sel_hi:[0,1,1]
	v_pk_fma_f32 v[110:111], v[130:131], v[248:249], v[110:111] op_sel_hi:[0,1,1]
	s_nop 0
	v_pk_fma_f32 v[110:111], v[132:133], v[168:169], v[110:111] op_sel_hi:[0,1,1]
	v_pk_fma_f32 v[112:113], v[132:133], v[166:167], v[112:113] op_sel_hi:[0,1,1]
	s_nop 0
	v_pk_fma_f32 v[112:113], v[134:135], v[170:171], v[112:113] op_sel_hi:[0,1,1]
	v_pk_fma_f32 v[110:111], v[134:135], v[172:173], v[110:111] op_sel_hi:[0,1,1]
	s_nop 0
	v_pk_fma_f32 v[110:111], v[108:109], v[176:177], v[110:111] op_sel_hi:[0,1,1]
	v_pk_fma_f32 v[108:109], v[108:109], v[174:175], v[112:113] op_sel_hi:[0,1,1]
	s_nop 0
	v_pk_fma_f32 v[112:113], v[136:137], v[178:179], v[108:109] op_sel_hi:[0,1,1]
	v_pk_fma_f32 v[104:105], v[136:137], v[180:181], v[110:111] op_sel_hi:[0,1,1]
	s_nop 0
	v_pk_fma_f32 v[104:105], v[102:103], v[194:195], v[104:105] op_sel_hi:[0,1,1]
	v_pk_fma_f32 v[102:103], v[102:103], v[192:193], v[112:113] op_sel_hi:[0,1,1]
	v_max_f32_e64 v63, -v102, 0
	v_mul_f32_e64 v102, |v102|, s43
	v_exp_f32_e32 v102, v102
	s_nop 0
	v_add_f32_e32 v102, 1.0, v102
	v_cmp_gt_f32_e32 vcc, s50, v102
	s_nop 1
	v_cndmask_b32_e64 v106, 0, 32, vcc
	v_ldexp_f32 v102, v102, v106
	v_log_f32_e32 v102, v102
	s_nop 0
	v_mul_f32_e32 v106, 0x3f317217, v102
	v_fma_f32 v106, v102, s51, -v106
	v_fmac_f32_e32 v106, 0x3377d1cf, v102
	v_fmac_f32_e32 v106, 0x3f317217, v102
	v_cmp_lt_f32_e64 s[0:1], |v102|, s65
	s_nop 1
	v_cndmask_b32_e64 v102, v102, v106, s[0:1]
	v_cndmask_b32_e32 v106, 0, v199, vcc
	v_sub_f32_e32 v102, v102, v106
	v_add_f32_e32 v63, v63, v102
	v_max_f32_e64 v102, -v103, 0
	v_mul_f32_e64 v103, |v103|, s43
	v_exp_f32_e32 v103, v103
	v_mul_f32_e32 v63, 0xbd800000, v63
	v_mul_f32_e32 v63, 0x3fb8aa3b, v63
	v_exp_f32_e32 v63, v63
	v_add_f32_e32 v103, 1.0, v103
	v_cmp_gt_f32_e32 vcc, s50, v103
	v_sub_f32_e32 v63, 1.0, v63
	s_nop 0
	v_cndmask_b32_e64 v106, 0, 32, vcc
	v_ldexp_f32 v103, v103, v106
	v_log_f32_e32 v103, v103
	s_nop 0
	v_mul_f32_e32 v106, 0x3f317217, v103
	v_fma_f32 v106, v103, s51, -v106
	v_fmac_f32_e32 v106, 0x3377d1cf, v103
	v_fmac_f32_e32 v106, 0x3f317217, v103
	v_cmp_lt_f32_e64 s[0:1], |v103|, s65
	s_nop 1
	v_cndmask_b32_e64 v103, v103, v106, s[0:1]
	v_cndmask_b32_e32 v106, 0, v199, vcc
	v_sub_f32_e32 v103, v103, v106
	v_add_f32_e32 v102, v102, v103
	v_max_f32_e64 v103, -v104, 0
	v_mul_f32_e64 v104, |v104|, s43
	v_exp_f32_e32 v104, v104
	v_mul_f32_e32 v102, 0xbd800000, v102
	v_mul_f32_e32 v102, 0x3fb8aa3b, v102
	v_exp_f32_e32 v102, v102
	v_add_f32_e32 v104, 1.0, v104
	v_cmp_gt_f32_e32 vcc, s50, v104
	v_sub_f32_e32 v102, 1.0, v102
	s_nop 0
	v_cndmask_b32_e64 v106, 0, 32, vcc
	v_ldexp_f32 v104, v104, v106
	v_log_f32_e32 v104, v104
	v_cvt_pk_bf16_f32 v102, v63, v102
	s_nop 0
	v_mul_f32_e32 v106, 0x3f317217, v104
	v_fma_f32 v106, v104, s51, -v106
	v_fmac_f32_e32 v106, 0x3377d1cf, v104
	v_fmac_f32_e32 v106, 0x3f317217, v104
	v_cmp_lt_f32_e64 s[0:1], |v104|, s65
	s_nop 1
	v_cndmask_b32_e64 v104, v104, v106, s[0:1]
	v_cndmask_b32_e32 v106, 0, v199, vcc
	v_sub_f32_e32 v104, v104, v106
	v_add_f32_e32 v103, v103, v104
	v_max_f32_e64 v104, -v105, 0
	v_mul_f32_e64 v105, |v105|, s43
	v_exp_f32_e32 v105, v105
	v_mul_f32_e32 v103, 0xbd800000, v103
	v_mul_f32_e32 v103, 0x3fb8aa3b, v103
	v_exp_f32_e32 v103, v103
	v_add_f32_e32 v105, 1.0, v105
	v_cmp_gt_f32_e32 vcc, s50, v105
	v_sub_f32_e32 v103, 1.0, v103
	s_nop 0
	v_cndmask_b32_e64 v106, 0, 32, vcc
	v_ldexp_f32 v105, v105, v106
	v_log_f32_e32 v105, v105
	s_nop 0
	v_mul_f32_e32 v106, 0x3f317217, v105
	v_fma_f32 v106, v105, s51, -v106
	v_fmac_f32_e32 v106, 0x3377d1cf, v105
	v_fmac_f32_e32 v106, 0x3f317217, v105
	v_cmp_lt_f32_e64 s[0:1], |v105|, s65
	s_nop 1
	v_cndmask_b32_e64 v105, v105, v106, s[0:1]
	v_cndmask_b32_e32 v106, 0, v199, vcc
	v_sub_f32_e32 v105, v105, v106
	v_add_f32_e32 v104, v104, v105
	v_mul_f32_e32 v104, 0xbd800000, v104
	v_mul_f32_e32 v104, 0x3fb8aa3b, v104
	v_exp_f32_e32 v104, v104
	v_readlane_b32 s0, v253, 26
	v_readlane_b32 s1, v253, 27
	v_cmp_lt_i32_e32 vcc, s53, v62
	v_sub_f32_e32 v104, 1.0, v104
	v_cvt_pk_bf16_f32 v103, v103, v104
	v_lshl_add_u64 v[104:105], s[22:23], 0, v[100:101]
	v_lshl_add_u64 v[92:93], v[92:93], 0, s[0:1]
	v_lshl_add_u64 v[98:99], v[98:99], 0, s[0:1]
	v_lshl_add_u64 v[100:101], v[100:101], 0, s[0:1]
	s_or_b64 s[30:31], vcc, s[30:31]
	global_store_dwordx2 v[104:105], v[102:103], off
	s_andn2_b64 exec, exec, s[30:31]
	s_cbranch_execz .LBB0_274
; __device__ __forceinline__ void prep2_phase(const Args& a, int e) {
;     ...
;     for (int m = gw; m < MT; m += ngw) {
;         const bf16* pr = PA + (size_t)m * APROJ;
;         float r[8], k[8], v[8], pq[8];
;         unpack8(*(const v4u*)(pr + c8), r); unpack8(*(const v4u*)(pr + 512 + c8), k); unpack8(*(const v4u*)(pr + 1024 + c8), v);
;         const int t = m < MP ? (m & (TPR - 1)) : ((m - MP) & (TSM - 1));
;         if (t > 0) {
;             unpack8(*(const v4u*)(pr - APROJ + c8), pq);
; #pragma unroll
;             for (int i = 0; i < 8; ++i) r[i] += (pq[i] - r[i]) * mur[i];
;             unpack8(*(const v4u*)(pr - APROJ + 512 + c8), pq);
; #pragma unroll
;             for (int i = 0; i < 8; ++i) k[i] += (pq[i] - k[i]) * muk[i];
;             unpack8(*(const v4u*)(pr - APROJ + 1024 + c8), pq);
; #pragma unroll
;             for (int i = 0; i < 8; ++i) v[i] += (pq[i] - v[i]) * muv[i];
;     ...
;         unpack8(*(const v4u*)(Lw + (size_t)m * 512 + c8), lw); unpack8(*(const v4u*)(La + (size_t)m * 512 + c8), la);
.LBB0_266:
	v_lshl_add_u64 v[156:157], s[22:23], 0, v[98:99]
	v_add_co_u32_e32 v110, vcc, 0x22c80000, v156
	v_cmp_lt_i32_e64 s[38:39], s59, v62
	s_nop 0
	v_addc_co_u32_e32 v111, vcc, 0, v157, vcc
	global_load_dwordx4 v[102:105], v[110:111], off
	global_load_dwordx4 v[106:109], v[110:111], off offset:1024
	s_nop 0
	global_load_dwordx4 v[110:113], v[110:111], off offset:2048
	v_lshl_add_u64 v[72:73], s[22:23], 0, v[96:97]
	s_mov_b32 s0, 0xe780000
	v_add_co_u32_e32 v74, vcc, s0, v72
	s_mov_b32 s0, 0x12880000
	s_nop 0
	v_addc_co_u32_e32 v75, vcc, 0, v73, vcc
	v_add_co_u32_e32 v76, vcc, s0, v72
	global_load_dwordx4 v[64:67], v[74:75], off
	s_nop 0
	v_addc_co_u32_e32 v77, vcc, 0, v73, vcc
	global_load_dwordx4 v[68:71], v[76:77], off
	v_add_co_u32_e32 v74, vcc, 0x22c7f000, v156
	s_nop 1
	v_addc_co_u32_e32 v75, vcc, 0, v157, vcc
	global_load_dwordx4 v[78:81], v[74:75], off offset:512
	global_load_dwordx4 v[82:85], v[74:75], off offset:1536
	global_load_dwordx4 v[86:89], v[74:75], off offset:2560
	v_lshl_add_u64 v[72:73], s[22:23], 0, v[92:93]
	v_lshl_add_u64 v[76:77], v[72:73], 0, s[68:69]
	v_add_co_u32_e32 v72, vcc, s42, v72
	s_nop 1
	v_addc_co_u32_e32 v73, vcc, 0, v73, vcc
	global_load_dwordx2 v[182:183], v[76:77], off offset:24
	global_load_dwordx4 v[72:75], v[72:73], off offset:3072
	global_load_dwordx2 v[76:77], v[76:77], off offset:16
	v_cmp_gt_i32_e32 vcc, s52, v62
	s_waitcnt vmcnt(10)
	v_lshlrev_b32_e32 v140, 16, v102
	v_cndmask_b32_e32 v63, 63, v198, vcc
	v_and_b32_e32 v63, v63, v62
	v_and_b32_e32 v141, 0xffff0000, v102
	v_lshlrev_b32_e32 v138, 16, v103
	v_and_b32_e32 v139, 0xffff0000, v103
	v_lshlrev_b32_e32 v134, 16, v104
	v_and_b32_e32 v135, 0xffff0000, v104
	v_lshlrev_b32_e32 v136, 16, v105
	v_and_b32_e32 v137, 0xffff0000, v105
	s_waitcnt vmcnt(9)
	v_lshlrev_b32_e32 v148, 16, v106
	v_and_b32_e32 v149, 0xffff0000, v106
	v_lshlrev_b32_e32 v146, 16, v107
	v_and_b32_e32 v147, 0xffff0000, v107
	v_lshlrev_b32_e32 v144, 16, v108
	v_and_b32_e32 v145, 0xffff0000, v108
	v_lshlrev_b32_e32 v142, 16, v109
	v_and_b32_e32 v143, 0xffff0000, v109
	s_waitcnt vmcnt(8)
	v_lshlrev_b32_e32 v132, 16, v110
	v_and_b32_e32 v133, 0xffff0000, v110
	v_lshlrev_b32_e32 v130, 16, v111
	v_and_b32_e32 v131, 0xffff0000, v111
	v_lshlrev_b32_e32 v128, 16, v112
	v_and_b32_e32 v129, 0xffff0000, v112
	v_lshlrev_b32_e32 v126, 16, v113
	v_and_b32_e32 v127, 0xffff0000, v113
	v_cmp_ne_u32_e32 vcc, 0, v63
	s_and_saveexec_b64 s[0:1], vcc
	s_xor_b64 s[0:1], exec, s[0:1]
	s_cbranch_execz .LBB0_268
	v_add_co_u32_e32 v116, vcc, 0x22c7f000, v156
	s_nop 1
	v_addc_co_u32_e32 v117, vcc, 0, v157, vcc
	s_waitcnt vmcnt(0)
	v_mov_b32_e32 v110, v78
	v_mov_b32_e32 v111, v79
	v_mov_b32_e32 v112, v80
	v_mov_b32_e32 v113, v81
	s_waitcnt vmcnt(0)
	v_lshlrev_b32_e32 v102, 16, v110
	v_and_b32_e32 v103, 0xffff0000, v110
	v_pk_add_f32 v[102:103], v[102:103], v[140:141] neg_lo:[0,1] neg_hi:[0,1]
	s_nop 0
	v_pk_fma_f32 v[106:107], v[6:7], v[102:103], v[140:141]
	v_lshlrev_b32_e32 v102, 16, v111
	v_and_b32_e32 v103, 0xffff0000, v111
	v_pk_add_f32 v[102:103], v[102:103], v[138:139] neg_lo:[0,1] neg_hi:[0,1]
	s_nop 0
	v_pk_fma_f32 v[104:105], v[8:9], v[102:103], v[138:139]
	v_lshlrev_b32_e32 v102, 16, v112
	v_and_b32_e32 v103, 0xffff0000, v112
	v_pk_add_f32 v[102:103], v[102:103], v[134:135] neg_lo:[0,1] neg_hi:[0,1]
	s_nop 0
	v_pk_fma_f32 v[110:111], v[2:3], v[102:103], v[134:135]
	v_lshlrev_b32_e32 v102, 16, v113
	v_and_b32_e32 v103, 0xffff0000, v113
	v_mov_b32_e32 v112, v82
	v_mov_b32_e32 v113, v83
	v_mov_b32_e32 v114, v84
	v_mov_b32_e32 v115, v85
	v_pk_add_f32 v[102:103], v[102:103], v[136:137] neg_lo:[0,1] neg_hi:[0,1]
	s_nop 0
	v_pk_fma_f32 v[108:109], v[4:5], v[102:103], v[136:137]
	v_mov_b32_e32 v134, v86
	v_mov_b32_e32 v135, v87
	v_mov_b32_e32 v136, v88
	v_mov_b32_e32 v137, v89
	s_waitcnt vmcnt(1)
	v_lshlrev_b32_e32 v102, 16, v112
	v_and_b32_e32 v103, 0xffff0000, v112
	v_pk_add_f32 v[102:103], v[102:103], v[148:149] neg_lo:[0,1] neg_hi:[0,1]
	s_waitcnt vmcnt(0)
	v_lshlrev_b32_e32 v112, 16, v134
	v_pk_fma_f32 v[124:125], v[14:15], v[102:103], v[148:149]
	v_lshlrev_b32_e32 v102, 16, v113
	v_and_b32_e32 v103, 0xffff0000, v113
	v_pk_add_f32 v[102:103], v[102:103], v[146:147] neg_lo:[0,1] neg_hi:[0,1]
	v_and_b32_e32 v113, 0xffff0000, v134
	v_pk_fma_f32 v[122:123], v[16:17], v[102:103], v[146:147]
	v_lshlrev_b32_e32 v102, 16, v114
	v_and_b32_e32 v103, 0xffff0000, v114
	v_pk_add_f32 v[102:103], v[102:103], v[144:145] neg_lo:[0,1] neg_hi:[0,1]
	v_lshlrev_b32_e32 v114, 16, v135
	v_pk_fma_f32 v[118:119], v[10:11], v[102:103], v[144:145]
	v_lshlrev_b32_e32 v102, 16, v115
	v_and_b32_e32 v103, 0xffff0000, v115
	v_and_b32_e32 v115, 0xffff0000, v135
	v_lshlrev_b32_e32 v116, 16, v136
	v_and_b32_e32 v117, 0xffff0000, v136
	v_lshlrev_b32_e32 v120, 16, v137
	v_and_b32_e32 v121, 0xffff0000, v137
	v_pk_add_f32 v[102:103], v[102:103], v[142:143] neg_lo:[0,1] neg_hi:[0,1]
	v_pk_add_f32 v[112:113], v[112:113], v[132:133] neg_lo:[0,1] neg_hi:[0,1]
	v_pk_add_f32 v[114:115], v[114:115], v[130:131] neg_lo:[0,1] neg_hi:[0,1]
	v_pk_add_f32 v[116:117], v[116:117], v[128:129] neg_lo:[0,1] neg_hi:[0,1]
	v_pk_add_f32 v[120:121], v[120:121], v[126:127] neg_lo:[0,1] neg_hi:[0,1]
	v_pk_fma_f32 v[102:103], v[12:13], v[102:103], v[142:143]
	v_pk_fma_f32 v[112:113], v[18:19], v[112:113], v[132:133]
	v_pk_fma_f32 v[114:115], v[20:21], v[114:115], v[130:131]
	v_pk_fma_f32 v[116:117], v[22:23], v[116:117], v[128:129]
	v_pk_fma_f32 v[120:121], v[24:25], v[120:121], v[126:127]
